# scan: next chunk's score-tile LDS reads and MFMAs interleaved with the current chunk's state update and output MFMAs inside one barrier segment
# speedup vs baseline: 1.0110x; 1.0110x over previous
; #define SCAN_BAR() asm volatile("s_waitcnt lgkmcnt(0)\n\ts_barrier" ::: "memory")
; __device__ void scan_phase(LAS unsigned char* lds, const Params& p) {
;     ...
;     for (int item = blockIdx.x; item < 256; item += gridDim.x) {
;         const int seq = (item & 7) + 8 * (item >> 5), es = (item >> 3) & 3;
;         const int dir = seq & 1, h = (seq >> 1) & 3, b = seq >> 3;
;         const char* Qx = (const char*)((const bf16_t*)(p.ws + (dir ? WS_QB : WS_QF)) + h * 128);
;         const char* Kx = (const char*)((const bf16_t*)(p.ws + (dir ? WS_KB : WS_KF)) + h * 128);
;         const char* Vx = (const char*)((const bf16_t*)(p.ws + WS_V) + h * 128 + es * 32);
;         const char* Rx = (const char*)(RT + (size_t)dir * NCHUNK * 512 + h * 128);
;         const char* Tx = (const char*)(RT + (size_t)(2 + dir) * NCHUNK * 512 + h * 128);
;         const unsigned qoff0 = (unsigned)((dir ? 63 - (tid >> 4) : (tid >> 4)) * 1024 + (tid & 15) * 16), qstep = dir ? (unsigned)-32768 : 32768u;
;         const unsigned voff = (unsigned)((dir ? 63 - (tid >> 3) : (tid >> 3)) * 1024 + (tid & 7) * 8), roff = (unsigned)(tid & 127) * 4u;
;         f32x4 S[2] = {(f32x4){0.f, 0.f, 0.f, 0.f}, (f32x4){0.f, 0.f, 0.f, 0.f}};
;         float tailp = 0.f;
;         u32x4 k4A[2], k4B[2], k4C[2], k4D[2]; u32x4 q4A[2], q4B[2], q4C[2], q4D[2]; u32x2 v4A, v4B, v4C, v4D; float rvA, tlA, rvB, tlB, rvC, tlC, rvD, tlD;
;     ...
;         SCAN_LOAD(0, k4A, q4A, v4A, rvA, tlA); SCAN_LOAD(1, k4B, q4B, v4B, rvB, tlB); SCAN_LOAD(2, k4C, q4C, v4C, rvC, tlC); SCAN_LOAD(3, k4D, q4D, v4D, rvD, tlD);
;         SCAN_STAGE(0, k4A, q4A, v4A, rvA, tlA); SCAN_LOAD(4, k4A, q4A, v4A, rvA, tlA);
;         SCAN_BAR();
.Lsc5_item:
	s_and_b32 s10, s9, 1
	s_lshr_b32 s3, s9, 1
	s_and_b32 s3, s3, 3
	s_lshr_b32 s4, s9, 5
	s_lshr_b32 s5, s9, 3
	s_and_b32 s5, s5, 3
	s_cmp_eq_u32 s10, 0
	s_cselect_b32 s15, 1, -1
	s_cselect_b32 s64, 0, 3
	s_cselect_b32 s65, -4, 0x43
	s_lshl_b32 s16, s4, 2
	s_add_u32 s16, s16, 0x200
	s_lshl_b32 s17, s4, 6
	s_add_u32 s16, s16, s64
	s_add_i32 s17, s17, s65
	s_lshl_b32 s3, s3, 8
	s_lshl_b32 s5, s5, 6
	s_cmp_eq_u32 s10, 0
	s_mov_b32 s65, 0x5100000
	s_cselect_b32 s64, s65, 0x7300000
	s_add_u32 s64, s64, s3
	s_add_u32 s18, s70, s64
	s_addc_u32 s19, s71, 0
	s_cmp_eq_u32 s10, 0
	s_mov_b32 s65, 0x9500000
	s_cselect_b32 s64, s65, 0xb700000
	s_add_u32 s64, s64, s3
	s_add_u32 s20, s70, s64
	s_addc_u32 s21, s71, 0
	s_add_u32 s64, s3, s5
	s_add_u32 s65, s64, 0xd900000
	s_add_u32 s22, s70, s65
	s_addc_u32 s23, s71, 0
	s_lshl_b32 s65, s10, 25
	s_add_u32 s64, s64, s65
	s_add_u32 s28, s68, s64
	s_addc_u32 s29, s69, 0
	s_mul_i32 s64, s10, 0x110000
	s_lshl_b32 s65, s3, 1
	s_add_u32 s64, s64, s65
	s_add_u32 s64, s64, 0x15b00000
	s_add_u32 s24, s70, s64
	s_addc_u32 s25, s71, 0
	s_add_u32 s26, s24, 0x220000
	s_addc_u32 s27, s25, 0
	s_lshl_b32 s64, s9, 16
	s_add_u32 s64, s64, 0xd00000
	s_add_u32 s30, s70, s64
	s_addc_u32 s31, s71, 0
	s_mul_i32 s5, s10, 63
	s_lshl_b32 s3, s7, 4
	v_add_u32_e32 v1, s3, v58
	v_xor_b32_e32 v1, s5, v1
	v_lshlrev_b32_e32 v1, 10, v1
	s_lshl_b32 s3, s8, 5
	v_lshl_add_u32 v57, v59, 3, v1
	v_add_u32_e32 v57, s3, v57
	v_lshrrev_b32_e32 v1, 4, v0
	v_xor_b32_e32 v93, s5, v1
	v_lshlrev_b32_e32 v93, 10, v93
	v_lshl_add_u32 v53, v58, 4, v93
	v_add_u32_e32 v1, 32, v1
	v_xor_b32_e32 v93, s5, v1
	v_lshlrev_b32_e32 v93, 10, v93
	v_lshl_add_u32 v54, v58, 4, v93
	v_lshrrev_b32_e32 v1, 3, v0
	v_xor_b32_e32 v1, s5, v1
	v_lshlrev_b32_e32 v1, 10, v1
	v_and_b32_e32 v93, 7, v0
	v_lshl_add_u32 v55, v93, 3, v1
	v_mov_b32_e32 v42, 0
	v_mov_b32_e32 v43, 0
	v_mov_b32_e32 v44, 0
	v_mov_b32_e32 v45, 0
	v_mov_b32_e32 v46, 0
	v_mov_b32_e32 v47, 0
	v_mov_b32_e32 v48, 0
	v_mov_b32_e32 v49, 0
	v_mov_b32_e32 v52, 0
	v_mov_b32_e32 v160, 0
	v_mov_b32_e32 v161, 0
	v_mov_b32_e32 v162, 0
	v_mov_b32_e32 v163, 0
	v_mov_b32_e32 v176, 0
	v_mov_b32_e32 v177, 0
	s_mov_b32 s3, 0
	s_cmp_lt_u32 s3, 4
	s_cselect_b32 s4, s16, s17
	s_mul_i32 s5, s3, s15
	s_add_i32 s4, s4, s5
	s_lshl_b32 s5, s4, 16
	s_lshl_b32 s4, s4, 11
	s_add_u32 s40, s18, s5
	s_addc_u32 s41, s19, 0
	s_add_u32 s42, s20, s5
	s_addc_u32 s43, s21, 0
	s_add_u32 s44, s22, s5
	s_addc_u32 s45, s23, 0
	s_add_u32 s46, s24, s4
	s_addc_u32 s47, s25, 0
	s_add_u32 s50, s26, s4
	s_addc_u32 s51, s27, 0
	global_load_dwordx4 v[2:5], v53, s[40:41]
	global_load_dwordx4 v[6:9], v54, s[40:41]
	global_load_dwordx4 v[10:13], v53, s[42:43]
	global_load_dwordx4 v[14:17], v54, s[42:43]
	global_load_dwordx2 v[18:19], v55, s[44:45]
	global_load_dword v20, v56, s[46:47]
	global_load_dword v21, v56, s[50:51]
	s_mov_b32 s3, 1
	s_cmp_lt_u32 s3, 4
	s_cselect_b32 s4, s16, s17
	s_mul_i32 s5, s3, s15
	s_add_i32 s4, s4, s5
	s_lshl_b32 s5, s4, 16
	s_lshl_b32 s4, s4, 11
	s_add_u32 s40, s18, s5
	s_addc_u32 s41, s19, 0
	s_add_u32 s42, s20, s5
	s_addc_u32 s43, s21, 0
	s_add_u32 s44, s22, s5
	s_addc_u32 s45, s23, 0
	s_add_u32 s46, s24, s4
	s_addc_u32 s47, s25, 0
	s_add_u32 s50, s26, s4
	s_addc_u32 s51, s27, 0
	global_load_dwordx4 v[22:25], v53, s[40:41]
	global_load_dwordx4 v[26:29], v54, s[40:41]
	global_load_dwordx4 v[30:33], v53, s[42:43]
	global_load_dwordx4 v[34:37], v54, s[42:43]
	global_load_dwordx2 v[38:39], v55, s[44:45]
	global_load_dword v40, v56, s[46:47]
	global_load_dword v41, v56, s[50:51]
	s_waitcnt vmcnt(0)
	ds_write_b128 v60, v[2:5] offset:0
	ds_write_b128 v60, v[6:9] offset:8704
	ds_write_b128 v60, v[10:13] offset:17408
	ds_write_b128 v60, v[14:17] offset:26112
	ds_write_b64 v63, v[18:19] offset:34816
	v_add_f32_e32 v92, v20, v52
	v_mul_f32_e32 v92, 0x3fb8aa3b, v92
	v_exp_f32_e32 v92, v92
	v_mov_b32_e32 v52, v21
	ds_write_b32 v78, v92 offset:0
	ds_write_b128 v61, v[22:25] offset:0
	ds_write_b128 v61, v[26:29] offset:8704
	ds_write_b128 v61, v[30:33] offset:17408
	ds_write_b128 v61, v[34:37] offset:26112
	ds_write_b64 v64, v[38:39] offset:34816
	v_add_f32_e32 v92, v40, v52
	v_mul_f32_e32 v92, 0x3fb8aa3b, v92
	v_exp_f32_e32 v92, v92
	v_mov_b32_e32 v52, v41
	ds_write_b32 v78, v92 offset:512
	s_mov_b32 s3, 2
	s_cmp_lt_u32 s3, 4
	s_cselect_b32 s4, s16, s17
	s_mul_i32 s5, s3, s15
	s_add_i32 s4, s4, s5
	s_lshl_b32 s5, s4, 16
	s_lshl_b32 s4, s4, 11
	s_add_u32 s40, s18, s5
	s_addc_u32 s41, s19, 0
	s_add_u32 s42, s20, s5
	s_addc_u32 s43, s21, 0
	s_add_u32 s44, s22, s5
	s_addc_u32 s45, s23, 0
	s_add_u32 s46, s24, s4
	s_addc_u32 s47, s25, 0
	s_add_u32 s50, s26, s4
	s_addc_u32 s51, s27, 0
	global_load_dwordx4 v[180:183], v53, s[40:41]
	global_load_dwordx4 v[184:187], v54, s[40:41]
	global_load_dwordx4 v[188:191], v53, s[42:43]
	global_load_dwordx4 v[192:195], v54, s[42:43]
	global_load_dwordx2 v[196:197], v55, s[44:45]
	global_load_dword v198, v56, s[46:47]
	global_load_dword v199, v56, s[50:51]
	global_store_dwordx2 v57, v[176:177], s[30:31]
	s_mov_b32 s3, 3
	s_cmp_lt_u32 s3, 4
	s_cselect_b32 s4, s16, s17
	s_mul_i32 s5, s3, s15
	s_add_i32 s4, s4, s5
	s_lshl_b32 s5, s4, 16
	s_lshl_b32 s4, s4, 11
	s_add_u32 s40, s18, s5
	s_addc_u32 s41, s19, 0
	s_add_u32 s42, s20, s5
	s_addc_u32 s43, s21, 0
	s_add_u32 s44, s22, s5
	s_addc_u32 s45, s23, 0
	s_add_u32 s46, s24, s4
	s_addc_u32 s47, s25, 0
	s_add_u32 s50, s26, s4
	s_addc_u32 s51, s27, 0
	global_load_dwordx4 v[2:5], v53, s[40:41]
	global_load_dwordx4 v[6:9], v54, s[40:41]
	global_load_dwordx4 v[10:13], v53, s[42:43]
	global_load_dwordx4 v[14:17], v54, s[42:43]
	global_load_dwordx2 v[18:19], v55, s[44:45]
	global_load_dword v20, v56, s[46:47]
	global_load_dword v21, v56, s[50:51]
	global_store_dwordx2 v57, v[176:177], s[30:31]
	s_waitcnt lgkmcnt(0)
	s_barrier
	ds_read_b32 v50, v79 offset:0
	ds_read_b32 v51, v79 offset:64
	ds_read_b128 v[96:99], v66 offset:0
	ds_read_b128 v[100:103], v66 offset:64
	ds_read_b128 v[104:107], v66 offset:128
	ds_read_b128 v[108:111], v66 offset:192
	s_cmp_eq_u32 s13, 0
	s_cbranch_scc1 .Lsc5_nox_p
	ds_read_b128 v[216:219], v69 offset:17408
	ds_read_b128 v[220:223], v69 offset:17472
	ds_read_b128 v[224:227], v69 offset:17536
	ds_read_b128 v[228:231], v69 offset:17600
.Lsc5_nox_p:
	s_cmp_eq_u32 s14, 0
	s_cbranch_scc1 .Lsc5_noy_p
	ds_read_b128 v[232:235], v69 offset:26112
	ds_read_b128 v[236:239], v69 offset:26176
	ds_read_b128 v[240:243], v69 offset:26240
	ds_read_b128 v[244:247], v69 offset:26304
.Lsc5_noy_p:
	s_waitcnt lgkmcnt(0)
	s_cmp_eq_u32 s13, 0
	s_cbranch_scc1 .Lsc5_nox2_p
	v_mfma_f32_16x16x32_bf16 v[152:155], v[216:219], v[96:99], 0
	v_mfma_f32_16x16x32_bf16 v[152:155], v[220:223], v[100:103], v[152:155]
	v_mfma_f32_16x16x32_bf16 v[152:155], v[224:227], v[104:107], v[152:155]
	v_mfma_f32_16x16x32_bf16 v[152:155], v[228:231], v[108:111], v[152:155]
.Lsc5_nox2_p:
	s_cmp_eq_u32 s14, 0
	s_cbranch_scc1 .Lsc5_noy2_p
	v_mfma_f32_16x16x32_bf16 v[156:159], v[232:235], v[96:99], 0
	v_mfma_f32_16x16x32_bf16 v[156:159], v[236:239], v[100:103], v[156:159]
	v_mfma_f32_16x16x32_bf16 v[156:159], v[240:243], v[104:107], v[156:159]
	v_mfma_f32_16x16x32_bf16 v[156:159], v[244:247], v[108:111], v[156:159]

.Lsc5_noy3_p:
	ds_write_b64 v84, v[160:161]
	ds_write_b64 v84, v[162:163] offset:1024
	s_waitcnt lgkmcnt(0)
	s_barrier
	s_mov_b32 s34, 0
.Lsc5_loop:
	ds_read_b32 v50, v79 offset:512
	ds_read_b32 v51, v79 offset:576
	ds_read_b64_tr_b16 v[128:129], v72 offset:34816
	ds_read_b64_tr_b16 v[130:131], v72 offset:35968
	ds_read_b64_tr_b16 v[132:133], v72 offset:37120
	ds_read_b64_tr_b16 v[134:135], v72 offset:38272
	ds_read_b64_tr_b16 v[136:137], v75 offset:17408
	ds_read_b64_tr_b16 v[138:139], v75 offset:21760
	ds_read_b64_tr_b16 v[140:141], v75 offset:17440
	ds_read_b64_tr_b16 v[142:143], v75 offset:21792
	ds_read_b64_tr_b16 v[144:145], v75 offset:26112
	ds_read_b64_tr_b16 v[146:147], v75 offset:30464
	ds_read_b64_tr_b16 v[148:149], v75 offset:26144
	ds_read_b64_tr_b16 v[150:151], v75 offset:30496
	s_add_u32 s3, s34, 4
	s_min_u32 s3, s3, 67
	s_cmp_lt_u32 s3, 4
	s_cselect_b32 s4, s16, s17
	s_mul_i32 s5, s3, s15
	s_add_i32 s4, s4, s5
	s_lshl_b32 s5, s4, 16
	s_lshl_b32 s4, s4, 11
	s_add_u32 s40, s18, s5
	s_addc_u32 s41, s19, 0
	s_add_u32 s42, s20, s5
	s_addc_u32 s43, s21, 0
	s_add_u32 s44, s22, s5
	s_addc_u32 s45, s23, 0
	s_add_u32 s46, s24, s4
	s_addc_u32 s47, s25, 0
	s_add_u32 s50, s26, s4
	s_addc_u32 s51, s27, 0
	global_load_dwordx4 v[22:25], v53, s[40:41]
	global_load_dwordx4 v[26:29], v54, s[40:41]
	global_load_dwordx4 v[30:33], v53, s[42:43]
	global_load_dwordx4 v[34:37], v54, s[42:43]
	global_load_dwordx2 v[38:39], v55, s[44:45]
	global_load_dword v40, v56, s[46:47]
	global_load_dword v41, v56, s[50:51]
	s_waitcnt lgkmcnt(6)
	v_mfma_f32_16x16x32_bf16 v[42:45], v[128:131], v[136:139], v[42:45]
	ds_read_b64_tr_b16 v[112:113], v82 offset:0
	ds_read_b64_tr_b16 v[114:115], v82 offset:288
	ds_read_b64_tr_b16 v[116:117], v82 offset:2304
	ds_read_b64_tr_b16 v[118:119], v82 offset:2592
	s_waitcnt lgkmcnt(8)
	v_mfma_f32_16x16x32_bf16 v[46:49], v[128:131], v[140:143], v[46:49]
	ds_read_b64_tr_b16 v[120:121], v82 offset:4608
	ds_read_b64_tr_b16 v[122:123], v82 offset:4896
	ds_read_b64_tr_b16 v[124:125], v82 offset:6912
	ds_read_b64_tr_b16 v[126:127], v82 offset:7200
	s_waitcnt lgkmcnt(10)
	v_mfma_f32_16x16x32_bf16 v[42:45], v[132:135], v[144:147], v[42:45]
	ds_read_b128 v[164:167], v86
	ds_read_b128 v[168:171], v86 offset:1024
	s_waitcnt lgkmcnt(10)
	v_mfma_f32_16x16x32_bf16 v[46:49], v[132:135], v[148:151], v[46:49]
	s_waitcnt lgkmcnt(8)
	v_mfma_f32_16x16x32_bf16 v[172:175], v[112:115], v[96:99], 0
	ds_read_b128 v[200:203], v67 offset:0
	ds_read_b128 v[204:207], v67 offset:64
	s_waitcnt lgkmcnt(8)
	v_mfma_f32_16x16x32_bf16 v[172:175], v[116:119], v[100:103], v[172:175]
	ds_read_b128 v[208:211], v67 offset:128
	ds_read_b128 v[212:215], v67 offset:192
	s_waitcnt lgkmcnt(8)
	v_mfma_f32_16x16x32_bf16 v[172:175], v[120:123], v[104:107], v[172:175]
	s_cmp_eq_u32 s13, 0
	s_cbranch_scc1 .Lsc5_nox_0
	ds_read_b128 v[216:219], v70 offset:17408
	ds_read_b128 v[220:223], v70 offset:17472
	ds_read_b128 v[224:227], v70 offset:17536
	ds_read_b128 v[228:231], v70 offset:17600
.Lsc5_nox_0:
	s_waitcnt lgkmcnt(6)
	v_mfma_f32_16x16x32_bf16 v[172:175], v[124:127], v[108:111], v[172:175]
	s_cmp_eq_u32 s14, 0
	s_cbranch_scc1 .Lsc5_noy_0
	ds_read_b128 v[232:235], v70 offset:26112
	ds_read_b128 v[236:239], v70 offset:26176
	ds_read_b128 v[240:243], v70 offset:26240
	ds_read_b128 v[244:247], v70 offset:26304
.Lsc5_noy_0:
	s_waitcnt lgkmcnt(5)
	v_mfma_f32_16x16x32_bf16 v[172:175], v[128:131], v[164:167], v[172:175]
	s_waitcnt lgkmcnt(4)
	s_cmp_eq_u32 s11, 0
	s_cbranch_scc1 .Lsc5_nopv1_0
	v_mfma_f32_16x16x32_bf16 v[172:175], v[132:135], v[168:171], v[172:175]
.Lsc5_nopv1_0:
	v_mul_f32_e32 v42, v42, v50
	v_mul_f32_e32 v43, v43, v50
	v_mul_f32_e32 v44, v44, v50
	v_mul_f32_e32 v45, v45, v50
	v_mul_f32_e32 v46, v46, v51
	v_mul_f32_e32 v47, v47, v51
	v_mul_f32_e32 v48, v48, v51
	v_mul_f32_e32 v49, v49, v51
	v_cvt_pk_bf16_f32 v88, v42, v43
	v_cvt_pk_bf16_f32 v89, v44, v45
	v_cvt_pk_bf16_f32 v90, v46, v47
	v_cvt_pk_bf16_f32 v91, v48, v49
	ds_write_b64 v81, v[88:89]
	ds_write_b64 v81, v[90:91] offset:1152
	s_add_u32 s3, s34, 0
	s_cmp_lt_u32 s3, 4
	s_cselect_b32 s4, s16, s17
	s_mul_i32 s5, s3, s15
	s_add_i32 s4, s4, s5
	s_lshl_b32 s4, s4, 16
	s_add_u32 s64, s28, s4
	s_addc_u32 s65, s29, 0
	s_cmp_eq_u32 s34, 0
	s_cselect_b32 s64, s30, s64
	s_cselect_b32 s65, s31, s65
	v_cvt_pk_bf16_f32 v176, v172, v173
	v_cvt_pk_bf16_f32 v177, v174, v175
	s_waitcnt lgkmcnt(0)
	s_cmp_eq_u32 s13, 0
	s_cbranch_scc1 .Lsc5_nox2_0
	v_mfma_f32_16x16x32_bf16 v[152:155], v[216:219], v[200:203], 0
	v_mfma_f32_16x16x32_bf16 v[152:155], v[220:223], v[204:207], v[152:155]
	v_mfma_f32_16x16x32_bf16 v[152:155], v[224:227], v[208:211], v[152:155]
	v_mfma_f32_16x16x32_bf16 v[152:155], v[228:231], v[212:215], v[152:155]
.Lsc5_nox2_0:
	s_cmp_eq_u32 s14, 0
	s_cbranch_scc1 .Lsc5_noy2_0
	v_mfma_f32_16x16x32_bf16 v[156:159], v[232:235], v[200:203], 0
	v_mfma_f32_16x16x32_bf16 v[156:159], v[236:239], v[204:207], v[156:159]
	v_mfma_f32_16x16x32_bf16 v[156:159], v[240:243], v[208:211], v[156:159]
	v_mfma_f32_16x16x32_bf16 v[156:159], v[244:247], v[212:215], v[156:159]
.Lsc5_noy2_0:
	s_waitcnt vmcnt(16)
	ds_write_b128 v62, v[180:183] offset:0
	ds_write_b128 v62, v[184:187] offset:8704
	ds_write_b128 v62, v[188:191] offset:17408
	ds_write_b128 v62, v[192:195] offset:26112
	ds_write_b64 v65, v[196:197] offset:34816
	v_add_f32_e32 v92, v198, v52
	v_mul_f32_e32 v92, 0x3fb8aa3b, v92
	v_exp_f32_e32 v92, v92
	v_mov_b32_e32 v52, v199
	ds_write_b32 v78, v92 offset:1024
	global_store_dwordx2 v57, v[176:177], s[64:65]
	s_cmp_eq_u32 s13, 0
	s_cbranch_scc1 .Lsc5_nox3_0
	v_cndmask_b32_e64 v152, 0, v152, s[76:77]
	v_cndmask_b32_e64 v153, 0, v153, s[78:79]
	v_cndmask_b32_e64 v154, 0, v154, s[80:81]
	v_cndmask_b32_e64 v155, 0, v155, s[82:83]
	v_cvt_pk_bf16_f32 v160, v152, v153
	v_cvt_pk_bf16_f32 v161, v154, v155

.Lsc5_noy3_0:
	ds_write_b64 v85, v[160:161]
	ds_write_b64 v85, v[162:163] offset:1024
	s_waitcnt lgkmcnt(0)
	s_barrier
	ds_read_b32 v50, v79 offset:1024
	ds_read_b32 v51, v79 offset:1088
	ds_read_b64_tr_b16 v[128:129], v73 offset:34816
	ds_read_b64_tr_b16 v[130:131], v73 offset:35968
	ds_read_b64_tr_b16 v[132:133], v73 offset:37120
	ds_read_b64_tr_b16 v[134:135], v73 offset:38272
	ds_read_b64_tr_b16 v[136:137], v76 offset:17408
	ds_read_b64_tr_b16 v[138:139], v76 offset:21760
	ds_read_b64_tr_b16 v[140:141], v76 offset:17440
	ds_read_b64_tr_b16 v[142:143], v76 offset:21792
	ds_read_b64_tr_b16 v[144:145], v76 offset:26112
	ds_read_b64_tr_b16 v[146:147], v76 offset:30464
	ds_read_b64_tr_b16 v[148:149], v76 offset:26144
	ds_read_b64_tr_b16 v[150:151], v76 offset:30496
	s_add_u32 s3, s34, 5
	s_min_u32 s3, s3, 67
	s_cmp_lt_u32 s3, 4
	s_cselect_b32 s4, s16, s17
	s_mul_i32 s5, s3, s15
	s_add_i32 s4, s4, s5
	s_lshl_b32 s5, s4, 16
	s_lshl_b32 s4, s4, 11
	s_add_u32 s40, s18, s5
	s_addc_u32 s41, s19, 0
	s_add_u32 s42, s20, s5
	s_addc_u32 s43, s21, 0
	s_add_u32 s44, s22, s5
	s_addc_u32 s45, s23, 0
	s_add_u32 s46, s24, s4
	s_addc_u32 s47, s25, 0
	s_add_u32 s50, s26, s4
	s_addc_u32 s51, s27, 0
	global_load_dwordx4 v[180:183], v53, s[40:41]
	global_load_dwordx4 v[184:187], v54, s[40:41]
	global_load_dwordx4 v[188:191], v53, s[42:43]
	global_load_dwordx4 v[192:195], v54, s[42:43]
	global_load_dwordx2 v[196:197], v55, s[44:45]
	global_load_dword v198, v56, s[46:47]
	global_load_dword v199, v56, s[50:51]
	s_waitcnt lgkmcnt(6)
	v_mfma_f32_16x16x32_bf16 v[42:45], v[128:131], v[136:139], v[42:45]
	ds_read_b64_tr_b16 v[112:113], v83 offset:0
	ds_read_b64_tr_b16 v[114:115], v83 offset:288
	ds_read_b64_tr_b16 v[116:117], v83 offset:2304
	ds_read_b64_tr_b16 v[118:119], v83 offset:2592
	s_waitcnt lgkmcnt(8)
	v_mfma_f32_16x16x32_bf16 v[46:49], v[128:131], v[140:143], v[46:49]
	ds_read_b64_tr_b16 v[120:121], v83 offset:4608
	ds_read_b64_tr_b16 v[122:123], v83 offset:4896
	ds_read_b64_tr_b16 v[124:125], v83 offset:6912
	ds_read_b64_tr_b16 v[126:127], v83 offset:7200
	s_waitcnt lgkmcnt(10)
	v_mfma_f32_16x16x32_bf16 v[42:45], v[132:135], v[144:147], v[42:45]
	ds_read_b128 v[164:167], v87
	ds_read_b128 v[168:171], v87 offset:1024
	s_waitcnt lgkmcnt(10)
	v_mfma_f32_16x16x32_bf16 v[46:49], v[132:135], v[148:151], v[46:49]
	s_waitcnt lgkmcnt(8)
	v_mfma_f32_16x16x32_bf16 v[172:175], v[112:115], v[200:203], 0
	ds_read_b128 v[96:99], v68 offset:0
	ds_read_b128 v[100:103], v68 offset:64
	s_waitcnt lgkmcnt(8)
	v_mfma_f32_16x16x32_bf16 v[172:175], v[116:119], v[204:207], v[172:175]
	ds_read_b128 v[104:107], v68 offset:128
	ds_read_b128 v[108:111], v68 offset:192
	s_waitcnt lgkmcnt(8)
	v_mfma_f32_16x16x32_bf16 v[172:175], v[120:123], v[208:211], v[172:175]
	s_cmp_eq_u32 s13, 0
	s_cbranch_scc1 .Lsc5_nox_1
	ds_read_b128 v[216:219], v71 offset:17408
	ds_read_b128 v[220:223], v71 offset:17472
	ds_read_b128 v[224:227], v71 offset:17536
	ds_read_b128 v[228:231], v71 offset:17600
.Lsc5_nox_1:
	s_waitcnt lgkmcnt(6)
	v_mfma_f32_16x16x32_bf16 v[172:175], v[124:127], v[212:215], v[172:175]
	s_cmp_eq_u32 s14, 0
	s_cbranch_scc1 .Lsc5_noy_1
	ds_read_b128 v[232:235], v71 offset:26112
	ds_read_b128 v[236:239], v71 offset:26176
	ds_read_b128 v[240:243], v71 offset:26240
	ds_read_b128 v[244:247], v71 offset:26304

.Lsc5_nopv1_1:
	v_mul_f32_e32 v42, v42, v50
	v_mul_f32_e32 v43, v43, v50
	v_mul_f32_e32 v44, v44, v50
	v_mul_f32_e32 v45, v45, v50
	v_mul_f32_e32 v46, v46, v51
	v_mul_f32_e32 v47, v47, v51
	v_mul_f32_e32 v48, v48, v51
	v_mul_f32_e32 v49, v49, v51
	v_cvt_pk_bf16_f32 v88, v42, v43
	v_cvt_pk_bf16_f32 v89, v44, v45
	v_cvt_pk_bf16_f32 v90, v46, v47
	v_cvt_pk_bf16_f32 v91, v48, v49
	ds_write_b64 v80, v[88:89]
	ds_write_b64 v80, v[90:91] offset:1152
	s_add_u32 s3, s34, 1
	s_cmp_lt_u32 s3, 4
	s_cselect_b32 s4, s16, s17
	s_mul_i32 s5, s3, s15
	s_add_i32 s4, s4, s5
	s_lshl_b32 s4, s4, 16
	s_add_u32 s64, s28, s4
	s_addc_u32 s65, s29, 0
	s_cmp_eq_u32 s34, 0
	s_cselect_b32 s64, s30, s64
	s_cselect_b32 s65, s31, s65
	v_cvt_pk_bf16_f32 v176, v172, v173
	v_cvt_pk_bf16_f32 v177, v174, v175
	s_waitcnt lgkmcnt(0)
	s_cmp_eq_u32 s13, 0
	s_cbranch_scc1 .Lsc5_nox2_1
	v_mfma_f32_16x16x32_bf16 v[152:155], v[216:219], v[96:99], 0
	v_mfma_f32_16x16x32_bf16 v[152:155], v[220:223], v[100:103], v[152:155]
	v_mfma_f32_16x16x32_bf16 v[152:155], v[224:227], v[104:107], v[152:155]
	v_mfma_f32_16x16x32_bf16 v[152:155], v[228:231], v[108:111], v[152:155]

.Lsc5_noy2_1:
	s_waitcnt vmcnt(16)
	ds_write_b128 v60, v[2:5] offset:0
	ds_write_b128 v60, v[6:9] offset:8704
	ds_write_b128 v60, v[10:13] offset:17408
	ds_write_b128 v60, v[14:17] offset:26112
	ds_write_b64 v63, v[18:19] offset:34816
	v_add_f32_e32 v92, v20, v52
	v_mul_f32_e32 v92, 0x3fb8aa3b, v92
	v_exp_f32_e32 v92, v92
	v_mov_b32_e32 v52, v21
	ds_write_b32 v78, v92 offset:0
	global_store_dwordx2 v57, v[176:177], s[64:65]
	s_cmp_eq_u32 s13, 0
	s_cbranch_scc1 .Lsc5_nox3_1
	v_cndmask_b32_e64 v152, 0, v152, s[76:77]
	v_cndmask_b32_e64 v153, 0, v153, s[78:79]
	v_cndmask_b32_e64 v154, 0, v154, s[80:81]
	v_cndmask_b32_e64 v155, 0, v155, s[82:83]
	v_cvt_pk_bf16_f32 v160, v152, v153
	v_cvt_pk_bf16_f32 v161, v154, v155

.Lsc5_noy3_1:
	ds_write_b64 v84, v[160:161]
	ds_write_b64 v84, v[162:163] offset:1024
	s_waitcnt lgkmcnt(0)
	s_barrier
	ds_read_b32 v50, v79 offset:0
	ds_read_b32 v51, v79 offset:64
	ds_read_b64_tr_b16 v[128:129], v74 offset:34816
	ds_read_b64_tr_b16 v[130:131], v74 offset:35968
	ds_read_b64_tr_b16 v[132:133], v74 offset:37120
	ds_read_b64_tr_b16 v[134:135], v74 offset:38272
	ds_read_b64_tr_b16 v[136:137], v77 offset:17408
	ds_read_b64_tr_b16 v[138:139], v77 offset:21760
	ds_read_b64_tr_b16 v[140:141], v77 offset:17440
	ds_read_b64_tr_b16 v[142:143], v77 offset:21792
	ds_read_b64_tr_b16 v[144:145], v77 offset:26112
	ds_read_b64_tr_b16 v[146:147], v77 offset:30464
	ds_read_b64_tr_b16 v[148:149], v77 offset:26144
	ds_read_b64_tr_b16 v[150:151], v77 offset:30496
	s_add_u32 s3, s34, 6
	s_min_u32 s3, s3, 67
	s_cmp_lt_u32 s3, 4
	s_cselect_b32 s4, s16, s17
	s_mul_i32 s5, s3, s15
	s_add_i32 s4, s4, s5
	s_lshl_b32 s5, s4, 16
	s_lshl_b32 s4, s4, 11
	s_add_u32 s40, s18, s5
	s_addc_u32 s41, s19, 0
	s_add_u32 s42, s20, s5
	s_addc_u32 s43, s21, 0
	s_add_u32 s44, s22, s5
	s_addc_u32 s45, s23, 0
	s_add_u32 s46, s24, s4
	s_addc_u32 s47, s25, 0
	s_add_u32 s50, s26, s4
	s_addc_u32 s51, s27, 0
	global_load_dwordx4 v[2:5], v53, s[40:41]
	global_load_dwordx4 v[6:9], v54, s[40:41]
	global_load_dwordx4 v[10:13], v53, s[42:43]
	global_load_dwordx4 v[14:17], v54, s[42:43]
	global_load_dwordx2 v[18:19], v55, s[44:45]
	global_load_dword v20, v56, s[46:47]
	global_load_dword v21, v56, s[50:51]
	s_waitcnt lgkmcnt(6)
	v_mfma_f32_16x16x32_bf16 v[42:45], v[128:131], v[136:139], v[42:45]
	ds_read_b64_tr_b16 v[112:113], v82 offset:0
	ds_read_b64_tr_b16 v[114:115], v82 offset:288
	ds_read_b64_tr_b16 v[116:117], v82 offset:2304
	ds_read_b64_tr_b16 v[118:119], v82 offset:2592
	s_waitcnt lgkmcnt(8)
	v_mfma_f32_16x16x32_bf16 v[46:49], v[128:131], v[140:143], v[46:49]
	ds_read_b64_tr_b16 v[120:121], v82 offset:4608
	ds_read_b64_tr_b16 v[122:123], v82 offset:4896
	ds_read_b64_tr_b16 v[124:125], v82 offset:6912
	ds_read_b64_tr_b16 v[126:127], v82 offset:7200
	s_waitcnt lgkmcnt(10)
	v_mfma_f32_16x16x32_bf16 v[42:45], v[132:135], v[144:147], v[42:45]
	ds_read_b128 v[164:167], v86
	ds_read_b128 v[168:171], v86 offset:1024
	s_waitcnt lgkmcnt(10)
	v_mfma_f32_16x16x32_bf16 v[46:49], v[132:135], v[148:151], v[46:49]
	s_waitcnt lgkmcnt(8)
	v_mfma_f32_16x16x32_bf16 v[172:175], v[112:115], v[96:99], 0
	ds_read_b128 v[200:203], v66 offset:0
	ds_read_b128 v[204:207], v66 offset:64
	s_waitcnt lgkmcnt(8)
	v_mfma_f32_16x16x32_bf16 v[172:175], v[116:119], v[100:103], v[172:175]
	ds_read_b128 v[208:211], v66 offset:128
	ds_read_b128 v[212:215], v66 offset:192
	s_waitcnt lgkmcnt(8)
	v_mfma_f32_16x16x32_bf16 v[172:175], v[120:123], v[104:107], v[172:175]
	s_cmp_eq_u32 s13, 0
	s_cbranch_scc1 .Lsc5_nox_2
	ds_read_b128 v[216:219], v69 offset:17408
	ds_read_b128 v[220:223], v69 offset:17472
	ds_read_b128 v[224:227], v69 offset:17536
	ds_read_b128 v[228:231], v69 offset:17600
.Lsc5_nox_2:
	s_waitcnt lgkmcnt(6)
	v_mfma_f32_16x16x32_bf16 v[172:175], v[124:127], v[108:111], v[172:175]
	s_cmp_eq_u32 s14, 0
	s_cbranch_scc1 .Lsc5_noy_2
	ds_read_b128 v[232:235], v69 offset:26112
	ds_read_b128 v[236:239], v69 offset:26176
	ds_read_b128 v[240:243], v69 offset:26240
	ds_read_b128 v[244:247], v69 offset:26304

.Lsc5_nopv1_2:
	v_mul_f32_e32 v42, v42, v50
	v_mul_f32_e32 v43, v43, v50
	v_mul_f32_e32 v44, v44, v50
	v_mul_f32_e32 v45, v45, v50
	v_mul_f32_e32 v46, v46, v51
	v_mul_f32_e32 v47, v47, v51
	v_mul_f32_e32 v48, v48, v51
	v_mul_f32_e32 v49, v49, v51
	v_cvt_pk_bf16_f32 v88, v42, v43
	v_cvt_pk_bf16_f32 v89, v44, v45
	v_cvt_pk_bf16_f32 v90, v46, v47
	v_cvt_pk_bf16_f32 v91, v48, v49
	ds_write_b64 v81, v[88:89]
	ds_write_b64 v81, v[90:91] offset:1152
	s_add_u32 s3, s34, 2
	s_cmp_lt_u32 s3, 4
	s_cselect_b32 s4, s16, s17
	s_mul_i32 s5, s3, s15
	s_add_i32 s4, s4, s5
	s_lshl_b32 s4, s4, 16
	s_add_u32 s64, s28, s4
	s_addc_u32 s65, s29, 0
	s_cmp_eq_u32 s34, 0
	s_cselect_b32 s64, s30, s64
	s_cselect_b32 s65, s31, s65
	v_cvt_pk_bf16_f32 v176, v172, v173
	v_cvt_pk_bf16_f32 v177, v174, v175
	s_waitcnt lgkmcnt(0)
	s_cmp_eq_u32 s13, 0
	s_cbranch_scc1 .Lsc5_nox2_2
	v_mfma_f32_16x16x32_bf16 v[152:155], v[216:219], v[200:203], 0
	v_mfma_f32_16x16x32_bf16 v[152:155], v[220:223], v[204:207], v[152:155]
	v_mfma_f32_16x16x32_bf16 v[152:155], v[224:227], v[208:211], v[152:155]
	v_mfma_f32_16x16x32_bf16 v[152:155], v[228:231], v[212:215], v[152:155]

.Lsc5_noy2_2:
	s_waitcnt vmcnt(16)
	ds_write_b128 v61, v[22:25] offset:0
	ds_write_b128 v61, v[26:29] offset:8704
	ds_write_b128 v61, v[30:33] offset:17408
	ds_write_b128 v61, v[34:37] offset:26112
	ds_write_b64 v64, v[38:39] offset:34816
	v_add_f32_e32 v92, v40, v52
	v_mul_f32_e32 v92, 0x3fb8aa3b, v92
	v_exp_f32_e32 v92, v92
	v_mov_b32_e32 v52, v41
	ds_write_b32 v78, v92 offset:512
	global_store_dwordx2 v57, v[176:177], s[64:65]
	s_cmp_eq_u32 s13, 0
	s_cbranch_scc1 .Lsc5_nox3_2
	v_cndmask_b32_e64 v152, 0, v152, s[76:77]
	v_cndmask_b32_e64 v153, 0, v153, s[78:79]
	v_cndmask_b32_e64 v154, 0, v154, s[80:81]
	v_cndmask_b32_e64 v155, 0, v155, s[82:83]
	v_cvt_pk_bf16_f32 v160, v152, v153
	v_cvt_pk_bf16_f32 v161, v154, v155

.Lsc5_noy3_2:
	ds_write_b64 v85, v[160:161]
	ds_write_b64 v85, v[162:163] offset:1024
	s_waitcnt lgkmcnt(0)
	s_barrier
	ds_read_b32 v50, v79 offset:512
	ds_read_b32 v51, v79 offset:576
	ds_read_b64_tr_b16 v[128:129], v72 offset:34816
	ds_read_b64_tr_b16 v[130:131], v72 offset:35968
	ds_read_b64_tr_b16 v[132:133], v72 offset:37120
	ds_read_b64_tr_b16 v[134:135], v72 offset:38272
	ds_read_b64_tr_b16 v[136:137], v75 offset:17408
	ds_read_b64_tr_b16 v[138:139], v75 offset:21760
	ds_read_b64_tr_b16 v[140:141], v75 offset:17440
	ds_read_b64_tr_b16 v[142:143], v75 offset:21792
	ds_read_b64_tr_b16 v[144:145], v75 offset:26112
	ds_read_b64_tr_b16 v[146:147], v75 offset:30464
	ds_read_b64_tr_b16 v[148:149], v75 offset:26144
	ds_read_b64_tr_b16 v[150:151], v75 offset:30496
	s_add_u32 s3, s34, 7
	s_min_u32 s3, s3, 67
	s_cmp_lt_u32 s3, 4
	s_cselect_b32 s4, s16, s17
	s_mul_i32 s5, s3, s15
	s_add_i32 s4, s4, s5
	s_lshl_b32 s5, s4, 16
	s_lshl_b32 s4, s4, 11
	s_add_u32 s40, s18, s5
	s_addc_u32 s41, s19, 0
	s_add_u32 s42, s20, s5
	s_addc_u32 s43, s21, 0
	s_add_u32 s44, s22, s5
	s_addc_u32 s45, s23, 0
	s_add_u32 s46, s24, s4
	s_addc_u32 s47, s25, 0
	s_add_u32 s50, s26, s4
	s_addc_u32 s51, s27, 0
	global_load_dwordx4 v[22:25], v53, s[40:41]
	global_load_dwordx4 v[26:29], v54, s[40:41]
	global_load_dwordx4 v[30:33], v53, s[42:43]
	global_load_dwordx4 v[34:37], v54, s[42:43]
	global_load_dwordx2 v[38:39], v55, s[44:45]
	global_load_dword v40, v56, s[46:47]
	global_load_dword v41, v56, s[50:51]
	s_waitcnt lgkmcnt(6)
	v_mfma_f32_16x16x32_bf16 v[42:45], v[128:131], v[136:139], v[42:45]
	ds_read_b64_tr_b16 v[112:113], v83 offset:0
	ds_read_b64_tr_b16 v[114:115], v83 offset:288
	ds_read_b64_tr_b16 v[116:117], v83 offset:2304
	ds_read_b64_tr_b16 v[118:119], v83 offset:2592
	s_waitcnt lgkmcnt(8)
	v_mfma_f32_16x16x32_bf16 v[46:49], v[128:131], v[140:143], v[46:49]
	ds_read_b64_tr_b16 v[120:121], v83 offset:4608
	ds_read_b64_tr_b16 v[122:123], v83 offset:4896
	ds_read_b64_tr_b16 v[124:125], v83 offset:6912
	ds_read_b64_tr_b16 v[126:127], v83 offset:7200
	s_waitcnt lgkmcnt(10)
	v_mfma_f32_16x16x32_bf16 v[42:45], v[132:135], v[144:147], v[42:45]
	ds_read_b128 v[164:167], v87
	ds_read_b128 v[168:171], v87 offset:1024
	s_waitcnt lgkmcnt(10)
	v_mfma_f32_16x16x32_bf16 v[46:49], v[132:135], v[148:151], v[46:49]
	s_waitcnt lgkmcnt(8)
	v_mfma_f32_16x16x32_bf16 v[172:175], v[112:115], v[200:203], 0
	ds_read_b128 v[96:99], v67 offset:0
	ds_read_b128 v[100:103], v67 offset:64
	s_waitcnt lgkmcnt(8)
	v_mfma_f32_16x16x32_bf16 v[172:175], v[116:119], v[204:207], v[172:175]
	ds_read_b128 v[104:107], v67 offset:128
	ds_read_b128 v[108:111], v67 offset:192
	s_waitcnt lgkmcnt(8)
	v_mfma_f32_16x16x32_bf16 v[172:175], v[120:123], v[208:211], v[172:175]
	s_cmp_eq_u32 s13, 0
	s_cbranch_scc1 .Lsc5_nox_3
	ds_read_b128 v[216:219], v70 offset:17408
	ds_read_b128 v[220:223], v70 offset:17472
	ds_read_b128 v[224:227], v70 offset:17536
	ds_read_b128 v[228:231], v70 offset:17600
.Lsc5_nox_3:
	s_waitcnt lgkmcnt(6)
	v_mfma_f32_16x16x32_bf16 v[172:175], v[124:127], v[212:215], v[172:175]
	s_cmp_eq_u32 s14, 0
	s_cbranch_scc1 .Lsc5_noy_3
	ds_read_b128 v[232:235], v70 offset:26112
	ds_read_b128 v[236:239], v70 offset:26176
	ds_read_b128 v[240:243], v70 offset:26240
	ds_read_b128 v[244:247], v70 offset:26304

.Lsc5_nopv1_3:
	v_mul_f32_e32 v42, v42, v50
	v_mul_f32_e32 v43, v43, v50
	v_mul_f32_e32 v44, v44, v50
	v_mul_f32_e32 v45, v45, v50
	v_mul_f32_e32 v46, v46, v51
	v_mul_f32_e32 v47, v47, v51
	v_mul_f32_e32 v48, v48, v51
	v_mul_f32_e32 v49, v49, v51
	v_cvt_pk_bf16_f32 v88, v42, v43
	v_cvt_pk_bf16_f32 v89, v44, v45
	v_cvt_pk_bf16_f32 v90, v46, v47
	v_cvt_pk_bf16_f32 v91, v48, v49
	ds_write_b64 v80, v[88:89]
	ds_write_b64 v80, v[90:91] offset:1152
	s_add_u32 s3, s34, 3
	s_cmp_lt_u32 s3, 4
	s_cselect_b32 s4, s16, s17
	s_mul_i32 s5, s3, s15
	s_add_i32 s4, s4, s5
	s_lshl_b32 s4, s4, 16
	s_add_u32 s64, s28, s4
	s_addc_u32 s65, s29, 0
	s_cmp_eq_u32 s34, 0
	s_cselect_b32 s64, s30, s64
	s_cselect_b32 s65, s31, s65
	v_cvt_pk_bf16_f32 v176, v172, v173
	v_cvt_pk_bf16_f32 v177, v174, v175
	s_waitcnt lgkmcnt(0)
	s_cmp_eq_u32 s13, 0
	s_cbranch_scc1 .Lsc5_nox2_3
	v_mfma_f32_16x16x32_bf16 v[152:155], v[216:219], v[96:99], 0
	v_mfma_f32_16x16x32_bf16 v[152:155], v[220:223], v[100:103], v[152:155]
	v_mfma_f32_16x16x32_bf16 v[152:155], v[224:227], v[104:107], v[152:155]
	v_mfma_f32_16x16x32_bf16 v[152:155], v[228:231], v[108:111], v[152:155]

.Lsc5_noy3_3:
	ds_write_b64 v84, v[160:161]
	ds_write_b64 v84, v[162:163] offset:1024
	s_waitcnt lgkmcnt(0)
	s_barrier
	ds_read_b32 v50, v79 offset:1024
	ds_read_b32 v51, v79 offset:1088
	ds_read_b64_tr_b16 v[128:129], v73 offset:34816
	ds_read_b64_tr_b16 v[130:131], v73 offset:35968
	ds_read_b64_tr_b16 v[132:133], v73 offset:37120
	ds_read_b64_tr_b16 v[134:135], v73 offset:38272
	ds_read_b64_tr_b16 v[136:137], v76 offset:17408
	ds_read_b64_tr_b16 v[138:139], v76 offset:21760
	ds_read_b64_tr_b16 v[140:141], v76 offset:17440
	ds_read_b64_tr_b16 v[142:143], v76 offset:21792
	ds_read_b64_tr_b16 v[144:145], v76 offset:26112
	ds_read_b64_tr_b16 v[146:147], v76 offset:30464
	ds_read_b64_tr_b16 v[148:149], v76 offset:26144
	ds_read_b64_tr_b16 v[150:151], v76 offset:30496
	s_add_u32 s3, s34, 8
	s_min_u32 s3, s3, 67
	s_cmp_lt_u32 s3, 4
	s_cselect_b32 s4, s16, s17
	s_mul_i32 s5, s3, s15
	s_add_i32 s4, s4, s5
	s_lshl_b32 s5, s4, 16
	s_lshl_b32 s4, s4, 11
	s_add_u32 s40, s18, s5
	s_addc_u32 s41, s19, 0
	s_add_u32 s42, s20, s5
	s_addc_u32 s43, s21, 0
	s_add_u32 s44, s22, s5
	s_addc_u32 s45, s23, 0
	s_add_u32 s46, s24, s4
	s_addc_u32 s47, s25, 0
	s_add_u32 s50, s26, s4
	s_addc_u32 s51, s27, 0
	global_load_dwordx4 v[180:183], v53, s[40:41]
	global_load_dwordx4 v[184:187], v54, s[40:41]
	global_load_dwordx4 v[188:191], v53, s[42:43]
	global_load_dwordx4 v[192:195], v54, s[42:43]
	global_load_dwordx2 v[196:197], v55, s[44:45]
	global_load_dword v198, v56, s[46:47]
	global_load_dword v199, v56, s[50:51]
	s_waitcnt lgkmcnt(6)
	v_mfma_f32_16x16x32_bf16 v[42:45], v[128:131], v[136:139], v[42:45]
	ds_read_b64_tr_b16 v[112:113], v82 offset:0
	ds_read_b64_tr_b16 v[114:115], v82 offset:288
	ds_read_b64_tr_b16 v[116:117], v82 offset:2304
	ds_read_b64_tr_b16 v[118:119], v82 offset:2592
	s_waitcnt lgkmcnt(8)
	v_mfma_f32_16x16x32_bf16 v[46:49], v[128:131], v[140:143], v[46:49]
	ds_read_b64_tr_b16 v[120:121], v82 offset:4608
	ds_read_b64_tr_b16 v[122:123], v82 offset:4896
	ds_read_b64_tr_b16 v[124:125], v82 offset:6912
	ds_read_b64_tr_b16 v[126:127], v82 offset:7200
	s_waitcnt lgkmcnt(10)
	v_mfma_f32_16x16x32_bf16 v[42:45], v[132:135], v[144:147], v[42:45]
	ds_read_b128 v[164:167], v86
	ds_read_b128 v[168:171], v86 offset:1024
	s_waitcnt lgkmcnt(10)
	v_mfma_f32_16x16x32_bf16 v[46:49], v[132:135], v[148:151], v[46:49]
	s_waitcnt lgkmcnt(8)
	v_mfma_f32_16x16x32_bf16 v[172:175], v[112:115], v[96:99], 0
	ds_read_b128 v[200:203], v68 offset:0
	ds_read_b128 v[204:207], v68 offset:64
	s_waitcnt lgkmcnt(8)
	v_mfma_f32_16x16x32_bf16 v[172:175], v[116:119], v[100:103], v[172:175]
	ds_read_b128 v[208:211], v68 offset:128
	ds_read_b128 v[212:215], v68 offset:192
	s_waitcnt lgkmcnt(8)
	v_mfma_f32_16x16x32_bf16 v[172:175], v[120:123], v[104:107], v[172:175]
	s_cmp_eq_u32 s13, 0
	s_cbranch_scc1 .Lsc5_nox_4
	ds_read_b128 v[216:219], v71 offset:17408
	ds_read_b128 v[220:223], v71 offset:17472
	ds_read_b128 v[224:227], v71 offset:17536
	ds_read_b128 v[228:231], v71 offset:17600
.Lsc5_nox_4:
	s_waitcnt lgkmcnt(6)
	v_mfma_f32_16x16x32_bf16 v[172:175], v[124:127], v[108:111], v[172:175]
	s_cmp_eq_u32 s14, 0
	s_cbranch_scc1 .Lsc5_noy_4
	ds_read_b128 v[232:235], v71 offset:26112
	ds_read_b128 v[236:239], v71 offset:26176
	ds_read_b128 v[240:243], v71 offset:26240
	ds_read_b128 v[244:247], v71 offset:26304

.Lsc5_nopv1_4:
	v_mul_f32_e32 v42, v42, v50
	v_mul_f32_e32 v43, v43, v50
	v_mul_f32_e32 v44, v44, v50
	v_mul_f32_e32 v45, v45, v50
	v_mul_f32_e32 v46, v46, v51
	v_mul_f32_e32 v47, v47, v51
	v_mul_f32_e32 v48, v48, v51
	v_mul_f32_e32 v49, v49, v51
	v_cvt_pk_bf16_f32 v88, v42, v43
	v_cvt_pk_bf16_f32 v89, v44, v45
	v_cvt_pk_bf16_f32 v90, v46, v47
	v_cvt_pk_bf16_f32 v91, v48, v49
	ds_write_b64 v81, v[88:89]
	ds_write_b64 v81, v[90:91] offset:1152
	s_add_u32 s3, s34, 4
	s_cmp_lt_u32 s3, 4
	s_cselect_b32 s4, s16, s17
	s_mul_i32 s5, s3, s15
	s_add_i32 s4, s4, s5
	s_lshl_b32 s4, s4, 16
	s_add_u32 s64, s28, s4
	s_addc_u32 s65, s29, 0
	v_cvt_pk_bf16_f32 v176, v172, v173
	v_cvt_pk_bf16_f32 v177, v174, v175
	s_waitcnt lgkmcnt(0)
	s_cmp_eq_u32 s13, 0
	s_cbranch_scc1 .Lsc5_nox2_4
	v_mfma_f32_16x16x32_bf16 v[152:155], v[216:219], v[200:203], 0
	v_mfma_f32_16x16x32_bf16 v[152:155], v[220:223], v[204:207], v[152:155]
	v_mfma_f32_16x16x32_bf16 v[152:155], v[224:227], v[208:211], v[152:155]
	v_mfma_f32_16x16x32_bf16 v[152:155], v[228:231], v[212:215], v[152:155]

.Lsc5_noy3_4:
	ds_write_b64 v85, v[160:161]
	ds_write_b64 v85, v[162:163] offset:1024
	s_waitcnt lgkmcnt(0)
	s_barrier
	ds_read_b32 v50, v79 offset:0
	ds_read_b32 v51, v79 offset:64
	ds_read_b64_tr_b16 v[128:129], v74 offset:34816
	ds_read_b64_tr_b16 v[130:131], v74 offset:35968
	ds_read_b64_tr_b16 v[132:133], v74 offset:37120
	ds_read_b64_tr_b16 v[134:135], v74 offset:38272
	ds_read_b64_tr_b16 v[136:137], v77 offset:17408
	ds_read_b64_tr_b16 v[138:139], v77 offset:21760
	ds_read_b64_tr_b16 v[140:141], v77 offset:17440
	ds_read_b64_tr_b16 v[142:143], v77 offset:21792
	ds_read_b64_tr_b16 v[144:145], v77 offset:26112
	ds_read_b64_tr_b16 v[146:147], v77 offset:30464
	ds_read_b64_tr_b16 v[148:149], v77 offset:26144
	ds_read_b64_tr_b16 v[150:151], v77 offset:30496
	s_add_u32 s3, s34, 9
	s_min_u32 s3, s3, 67
	s_cmp_lt_u32 s3, 4
	s_cselect_b32 s4, s16, s17
	s_mul_i32 s5, s3, s15
	s_add_i32 s4, s4, s5
	s_lshl_b32 s5, s4, 16
	s_lshl_b32 s4, s4, 11
	s_add_u32 s40, s18, s5
	s_addc_u32 s41, s19, 0
	s_add_u32 s42, s20, s5
	s_addc_u32 s43, s21, 0
	s_add_u32 s44, s22, s5
	s_addc_u32 s45, s23, 0
	s_add_u32 s46, s24, s4
	s_addc_u32 s47, s25, 0
	s_add_u32 s50, s26, s4
	s_addc_u32 s51, s27, 0
	global_load_dwordx4 v[2:5], v53, s[40:41]
	global_load_dwordx4 v[6:9], v54, s[40:41]
	global_load_dwordx4 v[10:13], v53, s[42:43]
	global_load_dwordx4 v[14:17], v54, s[42:43]
	global_load_dwordx2 v[18:19], v55, s[44:45]
	global_load_dword v20, v56, s[46:47]
	global_load_dword v21, v56, s[50:51]
	s_waitcnt lgkmcnt(6)
	v_mfma_f32_16x16x32_bf16 v[42:45], v[128:131], v[136:139], v[42:45]
	ds_read_b64_tr_b16 v[112:113], v83 offset:0
	ds_read_b64_tr_b16 v[114:115], v83 offset:288
	ds_read_b64_tr_b16 v[116:117], v83 offset:2304
	ds_read_b64_tr_b16 v[118:119], v83 offset:2592
	s_waitcnt lgkmcnt(8)
	v_mfma_f32_16x16x32_bf16 v[46:49], v[128:131], v[140:143], v[46:49]
	ds_read_b64_tr_b16 v[120:121], v83 offset:4608
	ds_read_b64_tr_b16 v[122:123], v83 offset:4896
	ds_read_b64_tr_b16 v[124:125], v83 offset:6912
	ds_read_b64_tr_b16 v[126:127], v83 offset:7200
	s_waitcnt lgkmcnt(10)
	v_mfma_f32_16x16x32_bf16 v[42:45], v[132:135], v[144:147], v[42:45]
	ds_read_b128 v[164:167], v87
	ds_read_b128 v[168:171], v87 offset:1024
	s_waitcnt lgkmcnt(10)
	v_mfma_f32_16x16x32_bf16 v[46:49], v[132:135], v[148:151], v[46:49]
	s_waitcnt lgkmcnt(8)
	v_mfma_f32_16x16x32_bf16 v[172:175], v[112:115], v[200:203], 0
	ds_read_b128 v[96:99], v66 offset:0
	ds_read_b128 v[100:103], v66 offset:64
	s_waitcnt lgkmcnt(8)
	v_mfma_f32_16x16x32_bf16 v[172:175], v[116:119], v[204:207], v[172:175]
	ds_read_b128 v[104:107], v66 offset:128
	ds_read_b128 v[108:111], v66 offset:192
	s_waitcnt lgkmcnt(8)
	v_mfma_f32_16x16x32_bf16 v[172:175], v[120:123], v[208:211], v[172:175]
	s_cmp_eq_u32 s13, 0
	s_cbranch_scc1 .Lsc5_nox_5
	ds_read_b128 v[216:219], v69 offset:17408
	ds_read_b128 v[220:223], v69 offset:17472
	ds_read_b128 v[224:227], v69 offset:17536
	ds_read_b128 v[228:231], v69 offset:17600
.Lsc5_nox_5:
	s_waitcnt lgkmcnt(6)
	v_mfma_f32_16x16x32_bf16 v[172:175], v[124:127], v[212:215], v[172:175]
	s_cmp_eq_u32 s14, 0
	s_cbranch_scc1 .Lsc5_noy_5
	ds_read_b128 v[232:235], v69 offset:26112
	ds_read_b128 v[236:239], v69 offset:26176
	ds_read_b128 v[240:243], v69 offset:26240
	ds_read_b128 v[244:247], v69 offset:26304

.Lsc5_nopv1_5:
	v_mul_f32_e32 v42, v42, v50
	v_mul_f32_e32 v43, v43, v50
	v_mul_f32_e32 v44, v44, v50
	v_mul_f32_e32 v45, v45, v50
	v_mul_f32_e32 v46, v46, v51
	v_mul_f32_e32 v47, v47, v51
	v_mul_f32_e32 v48, v48, v51
	v_mul_f32_e32 v49, v49, v51
	v_cvt_pk_bf16_f32 v88, v42, v43
	v_cvt_pk_bf16_f32 v89, v44, v45
	v_cvt_pk_bf16_f32 v90, v46, v47
	v_cvt_pk_bf16_f32 v91, v48, v49
	ds_write_b64 v80, v[88:89]
	ds_write_b64 v80, v[90:91] offset:1152
	s_add_u32 s3, s34, 5
	s_cmp_lt_u32 s3, 4
	s_cselect_b32 s4, s16, s17
	s_mul_i32 s5, s3, s15
	s_add_i32 s4, s4, s5
	s_lshl_b32 s4, s4, 16
	s_add_u32 s64, s28, s4
	s_addc_u32 s65, s29, 0
	v_cvt_pk_bf16_f32 v176, v172, v173
	v_cvt_pk_bf16_f32 v177, v174, v175
	s_waitcnt lgkmcnt(0)
	s_cmp_eq_u32 s13, 0
	s_cbranch_scc1 .Lsc5_nox2_5
	v_mfma_f32_16x16x32_bf16 v[152:155], v[216:219], v[96:99], 0
	v_mfma_f32_16x16x32_bf16 v[152:155], v[220:223], v[100:103], v[152:155]
	v_mfma_f32_16x16x32_bf16 v[152:155], v[224:227], v[104:107], v[152:155]
	v_mfma_f32_16x16x32_bf16 v[152:155], v[228:231], v[108:111], v[152:155]

; #define SCAN_BAR() asm volatile("s_waitcnt lgkmcnt(0)\n\ts_barrier" ::: "memory")
; __device__ void scan_phase(LAS unsigned char* lds, const Params& p) {
;     ...
;         for (int n0 = 0; n0 < 68; n0 += 4) {
;             SCAN_STAGE(1, k4B, q4B, v4B, rvB, tlB); SCAN_LOAD(min(n0 + 5, 67), k4B, q4B, v4B, rvB, tlB); SCAN_MAT(0, n0); SCAN_BAR();
;             SCAN_STAGE(0, k4C, q4C, v4C, rvC, tlC); SCAN_LOAD(min(n0 + 6, 67), k4C, q4C, v4C, rvC, tlC); SCAN_MAT(1, n0 + 1); SCAN_BAR();
;             SCAN_STAGE(1, k4D, q4D, v4D, rvD, tlD); SCAN_LOAD(min(n0 + 7, 67), k4D, q4D, v4D, rvD, tlD); SCAN_MAT(0, n0 + 2); SCAN_BAR();
;             SCAN_STAGE(0, k4A, q4A, v4A, rvA, tlA); SCAN_LOAD(min(n0 + 8, 67), k4A, q4A, v4A, rvA, tlA); SCAN_MAT(1, n0 + 3); SCAN_BAR();
;         }
.Lsc5_noy3_5:
	ds_write_b64 v84, v[160:161]
	ds_write_b64 v84, v[162:163] offset:1024
	s_waitcnt lgkmcnt(0)
	s_barrier
	s_add_u32 s34, s34, 6
	s_cmp_lt_u32 s34, 66
	s_cbranch_scc1 .Lsc5_loop
	ds_read_b32 v50, v79 offset:512
	ds_read_b32 v51, v79 offset:576
	ds_read_b64_tr_b16 v[128:129], v72 offset:34816
	ds_read_b64_tr_b16 v[130:131], v72 offset:35968
	ds_read_b64_tr_b16 v[132:133], v72 offset:37120
	ds_read_b64_tr_b16 v[134:135], v72 offset:38272
	ds_read_b64_tr_b16 v[136:137], v75 offset:17408
	ds_read_b64_tr_b16 v[138:139], v75 offset:21760
	ds_read_b64_tr_b16 v[140:141], v75 offset:17440
	ds_read_b64_tr_b16 v[142:143], v75 offset:21792
	ds_read_b64_tr_b16 v[144:145], v75 offset:26112
	ds_read_b64_tr_b16 v[146:147], v75 offset:30464
	ds_read_b64_tr_b16 v[148:149], v75 offset:26144
	ds_read_b64_tr_b16 v[150:151], v75 offset:30496
	s_add_u32 s3, s34, 4
	s_min_u32 s3, s3, 67
	s_cmp_lt_u32 s3, 4
	s_cselect_b32 s4, s16, s17
	s_mul_i32 s5, s3, s15
	s_add_i32 s4, s4, s5
	s_lshl_b32 s5, s4, 16
	s_lshl_b32 s4, s4, 11
	s_add_u32 s40, s18, s5
	s_addc_u32 s41, s19, 0
	s_add_u32 s42, s20, s5
	s_addc_u32 s43, s21, 0
	s_add_u32 s44, s22, s5
	s_addc_u32 s45, s23, 0
	s_add_u32 s46, s24, s4
	s_addc_u32 s47, s25, 0
	s_add_u32 s50, s26, s4
	s_addc_u32 s51, s27, 0
	global_load_dwordx4 v[22:25], v53, s[40:41]
	global_load_dwordx4 v[26:29], v54, s[40:41]
	global_load_dwordx4 v[30:33], v53, s[42:43]
	global_load_dwordx4 v[34:37], v54, s[42:43]
	global_load_dwordx2 v[38:39], v55, s[44:45]
	global_load_dword v40, v56, s[46:47]
	global_load_dword v41, v56, s[50:51]
	s_waitcnt lgkmcnt(6)
	v_mfma_f32_16x16x32_bf16 v[42:45], v[128:131], v[136:139], v[42:45]
	ds_read_b64_tr_b16 v[112:113], v82 offset:0
	ds_read_b64_tr_b16 v[114:115], v82 offset:288
	ds_read_b64_tr_b16 v[116:117], v82 offset:2304
	ds_read_b64_tr_b16 v[118:119], v82 offset:2592
	s_waitcnt lgkmcnt(8)
	v_mfma_f32_16x16x32_bf16 v[46:49], v[128:131], v[140:143], v[46:49]
	ds_read_b64_tr_b16 v[120:121], v82 offset:4608
	ds_read_b64_tr_b16 v[122:123], v82 offset:4896
	ds_read_b64_tr_b16 v[124:125], v82 offset:6912
	ds_read_b64_tr_b16 v[126:127], v82 offset:7200
	s_waitcnt lgkmcnt(10)
	v_mfma_f32_16x16x32_bf16 v[42:45], v[132:135], v[144:147], v[42:45]
	ds_read_b128 v[164:167], v86
	ds_read_b128 v[168:171], v86 offset:1024
	s_waitcnt lgkmcnt(10)
	v_mfma_f32_16x16x32_bf16 v[46:49], v[132:135], v[148:151], v[46:49]
	s_waitcnt lgkmcnt(8)
	v_mfma_f32_16x16x32_bf16 v[172:175], v[112:115], v[96:99], 0
	ds_read_b128 v[200:203], v67 offset:0
	ds_read_b128 v[204:207], v67 offset:64
	s_waitcnt lgkmcnt(8)
	v_mfma_f32_16x16x32_bf16 v[172:175], v[116:119], v[100:103], v[172:175]
	ds_read_b128 v[208:211], v67 offset:128
	ds_read_b128 v[212:215], v67 offset:192
	s_waitcnt lgkmcnt(8)
	v_mfma_f32_16x16x32_bf16 v[172:175], v[120:123], v[104:107], v[172:175]
	s_cmp_eq_u32 s13, 0
	s_cbranch_scc1 .Lsc5_nox_t0
	ds_read_b128 v[216:219], v70 offset:17408
	ds_read_b128 v[220:223], v70 offset:17472
	ds_read_b128 v[224:227], v70 offset:17536
	ds_read_b128 v[228:231], v70 offset:17600

.Lsc5_nopv1_t0:
	v_mul_f32_e32 v42, v42, v50
	v_mul_f32_e32 v43, v43, v50
	v_mul_f32_e32 v44, v44, v50
	v_mul_f32_e32 v45, v45, v50
	v_mul_f32_e32 v46, v46, v51
	v_mul_f32_e32 v47, v47, v51
	v_mul_f32_e32 v48, v48, v51
	v_mul_f32_e32 v49, v49, v51
	v_cvt_pk_bf16_f32 v88, v42, v43
	v_cvt_pk_bf16_f32 v89, v44, v45
	v_cvt_pk_bf16_f32 v90, v46, v47
	v_cvt_pk_bf16_f32 v91, v48, v49
	ds_write_b64 v81, v[88:89]
	ds_write_b64 v81, v[90:91] offset:1152
	s_add_u32 s3, s34, 0
	s_cmp_lt_u32 s3, 4
	s_cselect_b32 s4, s16, s17
	s_mul_i32 s5, s3, s15
	s_add_i32 s4, s4, s5
	s_lshl_b32 s4, s4, 16
	s_add_u32 s64, s28, s4
	s_addc_u32 s65, s29, 0
	v_cvt_pk_bf16_f32 v176, v172, v173
	v_cvt_pk_bf16_f32 v177, v174, v175
	s_waitcnt lgkmcnt(0)
	s_cmp_eq_u32 s13, 0
	s_cbranch_scc1 .Lsc5_nox2_t0
	v_mfma_f32_16x16x32_bf16 v[152:155], v[216:219], v[200:203], 0
	v_mfma_f32_16x16x32_bf16 v[152:155], v[220:223], v[204:207], v[152:155]
	v_mfma_f32_16x16x32_bf16 v[152:155], v[224:227], v[208:211], v[152:155]
	v_mfma_f32_16x16x32_bf16 v[152:155], v[228:231], v[212:215], v[152:155]

.Lsc5_noy3_t0:
	ds_write_b64 v85, v[160:161]
	ds_write_b64 v85, v[162:163] offset:1024
	s_waitcnt lgkmcnt(0)
	s_barrier
	ds_read_b64_tr_b16 v[128:129], v73 offset:34816
	ds_read_b64_tr_b16 v[130:131], v73 offset:35968
	ds_read_b64_tr_b16 v[132:133], v73 offset:37120
	ds_read_b64_tr_b16 v[134:135], v73 offset:38272
	ds_read_b64_tr_b16 v[136:137], v76 offset:17408
	ds_read_b64_tr_b16 v[138:139], v76 offset:21760
	ds_read_b64_tr_b16 v[140:141], v76 offset:17440
	ds_read_b64_tr_b16 v[142:143], v76 offset:21792
	ds_read_b64_tr_b16 v[144:145], v76 offset:26112
	ds_read_b64_tr_b16 v[146:147], v76 offset:30464
	ds_read_b64_tr_b16 v[148:149], v76 offset:26144
	ds_read_b64_tr_b16 v[150:151], v76 offset:30496
	s_add_u32 s3, s34, 5
	s_min_u32 s3, s3, 67
	s_cmp_lt_u32 s3, 4
	s_cselect_b32 s4, s16, s17
	s_mul_i32 s5, s3, s15
	s_add_i32 s4, s4, s5
	s_lshl_b32 s5, s4, 16
	s_lshl_b32 s4, s4, 11
	s_add_u32 s40, s18, s5
	s_addc_u32 s41, s19, 0
	s_add_u32 s42, s20, s5
	s_addc_u32 s43, s21, 0
	s_add_u32 s44, s22, s5
	s_addc_u32 s45, s23, 0
	s_add_u32 s46, s24, s4
	s_addc_u32 s47, s25, 0
	s_add_u32 s50, s26, s4
	s_addc_u32 s51, s27, 0
	global_load_dwordx4 v[180:183], v53, s[40:41]
	global_load_dwordx4 v[184:187], v54, s[40:41]
	global_load_dwordx4 v[188:191], v53, s[42:43]
	global_load_dwordx4 v[192:195], v54, s[42:43]
	global_load_dwordx2 v[196:197], v55, s[44:45]
	global_load_dword v198, v56, s[46:47]
	global_load_dword v199, v56, s[50:51]
	s_waitcnt lgkmcnt(6)
	v_mfma_f32_16x16x32_bf16 v[42:45], v[128:131], v[136:139], v[42:45]
	ds_read_b64_tr_b16 v[112:113], v83 offset:0
	ds_read_b64_tr_b16 v[114:115], v83 offset:288
	ds_read_b64_tr_b16 v[116:117], v83 offset:2304
	ds_read_b64_tr_b16 v[118:119], v83 offset:2592
	s_waitcnt lgkmcnt(8)
	v_mfma_f32_16x16x32_bf16 v[46:49], v[128:131], v[140:143], v[46:49]
	ds_read_b64_tr_b16 v[120:121], v83 offset:4608
	ds_read_b64_tr_b16 v[122:123], v83 offset:4896
	ds_read_b64_tr_b16 v[124:125], v83 offset:6912
	ds_read_b64_tr_b16 v[126:127], v83 offset:7200
	s_waitcnt lgkmcnt(10)
	v_mfma_f32_16x16x32_bf16 v[42:45], v[132:135], v[144:147], v[42:45]
	ds_read_b128 v[164:167], v87
	ds_read_b128 v[168:171], v87 offset:1024
	s_waitcnt lgkmcnt(10)
	v_mfma_f32_16x16x32_bf16 v[46:49], v[132:135], v[148:151], v[46:49]
	s_waitcnt lgkmcnt(8)
	v_mfma_f32_16x16x32_bf16 v[172:175], v[112:115], v[200:203], 0
	s_waitcnt lgkmcnt(6)
	v_mfma_f32_16x16x32_bf16 v[172:175], v[116:119], v[204:207], v[172:175]
	s_waitcnt lgkmcnt(4)
	v_mfma_f32_16x16x32_bf16 v[172:175], v[120:123], v[208:211], v[172:175]
	s_waitcnt lgkmcnt(2)
	v_mfma_f32_16x16x32_bf16 v[172:175], v[124:127], v[212:215], v[172:175]
	s_waitcnt lgkmcnt(1)
	v_mfma_f32_16x16x32_bf16 v[172:175], v[128:131], v[164:167], v[172:175]
	s_waitcnt lgkmcnt(0)
	s_cmp_eq_u32 s11, 0
	s_cbranch_scc1 .Lsc5_nopv1_t1
	v_mfma_f32_16x16x32_bf16 v[172:175], v[132:135], v[168:171], v[172:175]
.Lsc5_nopv1_t1:
	s_add_u32 s3, s34, 1
	s_cmp_lt_u32 s3, 4
	s_cselect_b32 s4, s16, s17
	s_mul_i32 s5, s3, s15
	s_add_i32 s4, s4, s5
	s_lshl_b32 s4, s4, 16
	s_add_u32 s64, s28, s4
	s_addc_u32 s65, s29, 0
	s_nop 7
	v_cvt_pk_bf16_f32 v176, v172, v173
	v_cvt_pk_bf16_f32 v177, v174, v175
	s_waitcnt vmcnt(16)
	ds_write_b128 v60, v[2:5] offset:0
	ds_write_b128 v60, v[6:9] offset:8704
	ds_write_b128 v60, v[10:13] offset:17408
	ds_write_b128 v60, v[14:17] offset:26112
	ds_write_b64 v63, v[18:19] offset:34816
	v_add_f32_e32 v92, v20, v52
	v_mul_f32_e32 v92, 0x3fb8aa3b, v92
	v_exp_f32_e32 v92, v92
	v_mov_b32_e32 v52, v21
	ds_write_b32 v78, v92 offset:0
	global_store_dwordx2 v57, v[176:177], s[64:65]
	s_waitcnt lgkmcnt(0)
	s_barrier
	s_add_u32 s9, s9, s35
	s_cmp_lt_u32 s9, 0x100
	s_cbranch_scc1 .Lsc5_item
